# combination: attention K/V staging loads behind QK^T MFMAs + chunk_local image-loop loads one iteration ahead + GEMM group 2 first iteration with C=0 (no accumulator zeroing, relaxed first two waits)
# speedup vs baseline: 1.0033x; 1.0021x over previous
.LBB0_645:
	v_add_u32_e32 v8, s3, v221
	ds_read_b128 v[2:5], v8
	v_add_co_u32_e32 v6, vcc, 0xffff5000, v0
	s_addk_i32 s3, 0x800
	s_nop 0
	v_addc_co_u32_e32 v7, vcc, -1, v1, vcc
	s_waitcnt lgkmcnt(0)
	global_store_dwordx4 v[6:7], v[2:5], off
	ds_read_b128 v[2:5], v8 offset:1024
	s_cmpk_lg_i32 s3, 0x2000
	s_waitcnt lgkmcnt(0)
	global_store_dwordx4 v[0:1], v[2:5], off
	v_lshl_add_u64 v[0:1], v[0:1], 0, s[72:73]
	s_cbranch_scc1 .LBB0_645
	s_waitcnt lgkmcnt(0)
	v_mov_b32_e32 v0, s63
	ds_read_b32 v52, v0 offset:17660
	s_lshl_b32 s3, s13, 14
	s_lshl_b64 s[6:7], s[78:79], 19
	s_or_b32 s6, s6, s3
	v_lshl_add_u64 v[40:41], v[128:129], 0, s[6:7]
	v_lshl_add_u64 v[42:43], v[130:131], 0, s[6:7]
	v_lshl_add_u64 v[44:45], v[132:133], 0, s[6:7]
	s_mov_b64 s[78:79], 0
	s_mov_b32 s3, 0
	v_mov_b32_e32 v53, v223
	v_mov_b32_e32 v54, v222
	s_mov_b32 s6, 0
	v_lshl_add_u64 v[82:83], v[44:45], 0, s[78:79]
	v_add_co_u32_e32 v82, vcc, 0x1a000000, v82
	s_nop 1
	v_addc_co_u32_e32 v83, vcc, 0, v83, vcc
	global_load_dwordx4 v[84:87], v[82:83], off
	global_load_dwordx4 v[88:91], v[82:83], off offset:16
	global_load_dwordx4 v[108:111], v[82:83], off offset:2048
	global_load_dwordx4 v[112:115], v[82:83], off offset:2064
	v_lshl_add_u64 v[82:83], v[44:45], 0, s[78:79]
	v_add_co_u32_e32 v82, vcc, 0x1c000000, v82
	s_nop 1
	v_addc_co_u32_e32 v83, vcc, 0, v83, vcc
	global_load_dwordx4 v[92:95], v[82:83], off
	global_load_dwordx4 v[96:99], v[82:83], off offset:16
	global_load_dwordx4 v[116:119], v[82:83], off offset:2048
	global_load_dwordx4 v[144:147], v[82:83], off offset:2064
	v_lshl_add_u64 v[82:83], v[44:45], 0, s[78:79]
	v_add_co_u32_e32 v82, vcc, 0x1e000000, v82
	s_nop 1
	v_addc_co_u32_e32 v83, vcc, 0, v83, vcc
	global_load_dwordx4 v[100:103], v[82:83], off
	global_load_dwordx4 v[104:107], v[82:83], off offset:16
	global_load_dwordx4 v[244:247], v[82:83], off offset:2048
	global_load_dwordx4 v[248:251], v[82:83], off offset:2064
.LBB0_647:
	v_lshl_add_u64 v[0:1], v[44:45], 0, s[78:79]
	v_add_co_u32_e32 v2, vcc, 0x1a000000, v0
	v_and_or_b32 v46, s6, 4, v151
	s_nop 0
	v_addc_co_u32_e32 v3, vcc, 0, v1, vcc
	v_add_co_u32_e32 v4, vcc, 0x1c000000, v0
	v_and_or_b32 v55, s3, 32, v46
	s_nop 0
	v_addc_co_u32_e32 v5, vcc, 0, v1, vcc
	v_add_co_u32_e32 v48, vcc, 0x1e000000, v0
	s_mov_b32 s7, 0x1a000000
	s_nop 0
	v_addc_co_u32_e32 v49, vcc, 0, v1, vcc
	s_nop 0
	s_cmp_eq_u32 s78, 0
	s_cbranch_scc1 .Lcl_pf_first
	s_waitcnt vmcnt(20)
	s_branch .Lcl_pf_ok

.Lcl_pf_ok:
	v_mov_b32_e32 v56, v84
	v_mov_b32_e32 v57, v85
	v_mov_b32_e32 v58, v86
	v_mov_b32_e32 v59, v87
	v_mov_b32_e32 v60, v88
	v_mov_b32_e32 v61, v89
	v_mov_b32_e32 v62, v90
	v_mov_b32_e32 v63, v91
	v_mov_b32_e32 v36, v92
	v_mov_b32_e32 v37, v93
	v_mov_b32_e32 v38, v94
	v_mov_b32_e32 v39, v95
	v_mov_b32_e32 v32, v96
	v_mov_b32_e32 v33, v97
	v_mov_b32_e32 v34, v98
	v_mov_b32_e32 v35, v99
	v_mov_b32_e32 v28, v100
	v_mov_b32_e32 v29, v101
	v_mov_b32_e32 v30, v102
	v_mov_b32_e32 v31, v103
	v_mov_b32_e32 v24, v104
	v_mov_b32_e32 v25, v105
	v_mov_b32_e32 v26, v106
	v_mov_b32_e32 v27, v107
	v_mov_b32_e32 v20, v108
	v_mov_b32_e32 v21, v109
	v_mov_b32_e32 v22, v110
	v_mov_b32_e32 v23, v111
	v_mov_b32_e32 v16, v112
	v_mov_b32_e32 v17, v113
	v_mov_b32_e32 v18, v114
	v_mov_b32_e32 v19, v115
	v_mov_b32_e32 v12, v116
	v_mov_b32_e32 v13, v117
	v_mov_b32_e32 v14, v118
	v_mov_b32_e32 v15, v119
	v_mov_b32_e32 v8, v144
	v_mov_b32_e32 v9, v145
	v_mov_b32_e32 v10, v146
	v_mov_b32_e32 v11, v147
	v_mov_b32_e32 v0, v244
	v_mov_b32_e32 v1, v245
	v_mov_b32_e32 v2, v246
	v_mov_b32_e32 v3, v247
	v_mov_b32_e32 v4, v248
	v_mov_b32_e32 v5, v249
	v_mov_b32_e32 v6, v250
	v_mov_b32_e32 v7, v251
	s_cmpk_eq_i32 s78, 0x3000
	s_cbranch_scc1 .Lcl_pf_skip
	v_lshl_add_u64 v[82:83], v[44:45], 0, s[78:79]
	v_add_co_u32_e32 v82, vcc, 0x1a001000, v82
	s_nop 1
	v_addc_co_u32_e32 v83, vcc, 0, v83, vcc
	global_load_dwordx4 v[84:87], v[82:83], off
	global_load_dwordx4 v[88:91], v[82:83], off offset:16
	global_load_dwordx4 v[108:111], v[82:83], off offset:2048
	global_load_dwordx4 v[112:115], v[82:83], off offset:2064
	v_lshl_add_u64 v[82:83], v[44:45], 0, s[78:79]
	v_add_co_u32_e32 v82, vcc, 0x1c001000, v82
	s_nop 1
	v_addc_co_u32_e32 v83, vcc, 0, v83, vcc
	global_load_dwordx4 v[92:95], v[82:83], off
	global_load_dwordx4 v[96:99], v[82:83], off offset:16
	global_load_dwordx4 v[116:119], v[82:83], off offset:2048
	global_load_dwordx4 v[144:147], v[82:83], off offset:2064
	v_lshl_add_u64 v[82:83], v[44:45], 0, s[78:79]
	v_add_co_u32_e32 v82, vcc, 0x1e001000, v82
	s_nop 1
	v_addc_co_u32_e32 v83, vcc, 0, v83, vcc
	global_load_dwordx4 v[100:103], v[82:83], off
	global_load_dwordx4 v[104:107], v[82:83], off offset:16
	global_load_dwordx4 v[244:247], v[82:83], off offset:2048
	global_load_dwordx4 v[248:251], v[82:83], off offset:2064
.Lcl_pf_skip:
	ds_read2_b32 v[50:51], v54 offset1:8
	ds_read2_b32 v[46:47], v54 offset0:64 offset1:72
	v_add_u32_e32 v54, 64, v54
	s_waitcnt lgkmcnt(1)
	v_mul_f32_e32 v64, 0x3fb8aa3b, v50
	v_exp_f32_e32 v64, v64
	v_sub_f32_e32 v50, v52, v50
	v_mul_f32_e32 v50, 0x3fb8aa3b, v50
	v_exp_f32_e32 v80, v50
	s_waitcnt lgkmcnt(0)
	v_mul_f32_e64 v50, v46, -v64
	v_and_b32_e32 v69, 0xffff0000, v57
	v_lshlrev_b32_e32 v68, 16, v57
	v_and_b32_e32 v67, 0xffff0000, v56
	v_lshlrev_b32_e32 v66, 16, v56
	v_pk_mul_f32 v[56:57], v[64:65], v[68:69] op_sel_hi:[0,1]
	v_and_b32_e32 v69, 0xffff0000, v58
	v_lshlrev_b32_e32 v68, 16, v58
	v_and_b32_e32 v71, 0xffff0000, v59
	v_lshlrev_b32_e32 v70, 16, v59
	v_pk_mul_f32 v[66:67], v[64:65], v[66:67] op_sel_hi:[0,1]
	v_pk_mul_f32 v[68:69], v[64:65], v[68:69] op_sel_hi:[0,1]
	v_pk_mul_f32 v[58:59], v[64:65], v[70:71] op_sel_hi:[0,1]
	v_cvt_pk_bf16_f32 v66, v66, v67
	v_cvt_pk_bf16_f32 v67, v56, v57
	v_cvt_pk_bf16_f32 v56, v68, v69
	v_cvt_pk_bf16_f32 v57, v58, v59
	v_and_b32_e32 v59, 0xffff0000, v60
	v_lshlrev_b32_e32 v58, 16, v60
	v_and_b32_e32 v69, 0xffff0000, v61
	v_lshlrev_b32_e32 v68, 16, v61
	v_and_b32_e32 v71, 0xffff0000, v63
	v_lshlrev_b32_e32 v70, 16, v63
	v_pk_mul_f32 v[58:59], v[64:65], v[58:59] op_sel_hi:[0,1]
	v_pk_mul_f32 v[60:61], v[64:65], v[68:69] op_sel_hi:[0,1]
	v_and_b32_e32 v69, 0xffff0000, v62
	v_lshlrev_b32_e32 v68, 16, v62
	v_pk_mul_f32 v[62:63], v[64:65], v[70:71] op_sel_hi:[0,1]
	v_pk_mul_f32 v[68:69], v[64:65], v[68:69] op_sel_hi:[0,1]
	v_cvt_pk_bf16_f32 v58, v58, v59
	v_cvt_pk_bf16_f32 v59, v60, v61
	v_cvt_pk_bf16_f32 v61, v62, v63
	v_lshl_add_u64 v[62:63], v[42:43], 0, s[78:79]
	v_cvt_pk_bf16_f32 v60, v68, v69
	v_add_co_u32_e32 v68, vcc, s7, v62
	v_and_b32_e32 v71, 0xffff0000, v39
	v_addc_co_u32_e32 v69, vcc, 0, v63, vcc
	global_store_dwordx2 v[68:69], v[66:67], off
	global_store_dwordx2 v[68:69], v[56:57], off offset:16
	global_store_dwordx2 v[68:69], v[58:59], off offset:32
	global_store_dwordx2 v[68:69], v[60:61], off offset:48
	v_and_b32_e32 v57, 0xffff0000, v36
	v_lshlrev_b32_e32 v56, 16, v36
	v_and_b32_e32 v61, 0xffff0000, v37
	v_lshlrev_b32_e32 v60, 16, v37
	v_lshlrev_b32_e32 v70, 16, v39
	v_pk_mul_f32 v[58:59], v[50:51], v[56:57] op_sel_hi:[0,1]
	v_pk_mul_f32 v[36:37], v[50:51], v[60:61] op_sel_hi:[0,1]
	v_and_b32_e32 v65, 0xffff0000, v38
	v_lshlrev_b32_e32 v64, 16, v38
	v_pk_mul_f32 v[38:39], v[50:51], v[70:71] op_sel_hi:[0,1]
	v_pk_mul_f32 v[66:67], v[50:51], v[64:65] op_sel_hi:[0,1]
	v_cvt_pk_bf16_f32 v58, v58, v59
	v_cvt_pk_bf16_f32 v59, v36, v37
	v_cvt_pk_bf16_f32 v37, v38, v39
	v_and_b32_e32 v39, 0xffff0000, v32
	v_lshlrev_b32_e32 v38, 16, v32
	v_and_b32_e32 v73, 0xffff0000, v33
	v_lshlrev_b32_e32 v72, 16, v33
	v_and_b32_e32 v79, 0xffff0000, v35
	v_lshlrev_b32_e32 v78, 16, v35
	v_cvt_pk_bf16_f32 v36, v66, v67
	v_pk_mul_f32 v[66:67], v[50:51], v[38:39] op_sel_hi:[0,1]
	v_pk_mul_f32 v[32:33], v[50:51], v[72:73] op_sel_hi:[0,1]
	v_and_b32_e32 v75, 0xffff0000, v34
	v_lshlrev_b32_e32 v74, 16, v34
	v_pk_mul_f32 v[34:35], v[50:51], v[78:79] op_sel_hi:[0,1]
	s_brev_b32 s7, 56
	v_pk_mul_f32 v[76:77], v[50:51], v[74:75] op_sel_hi:[0,1]
	v_cvt_pk_bf16_f32 v66, v66, v67
	v_cvt_pk_bf16_f32 v67, v32, v33
	v_cvt_pk_bf16_f32 v33, v34, v35
	v_add_co_u32_e32 v34, vcc, s7, v62
	v_cvt_pk_bf16_f32 v32, v76, v77
	s_nop 0
	v_addc_co_u32_e32 v35, vcc, 0, v63, vcc
	global_store_dwordx2 v[34:35], v[58:59], off
	global_store_dwordx2 v[34:35], v[36:37], off offset:16
	global_store_dwordx2 v[34:35], v[66:67], off offset:32
	global_store_dwordx2 v[34:35], v[32:33], off offset:48
	v_and_b32_e32 v33, 0xffff0000, v28
	v_lshlrev_b32_e32 v32, 16, v28
	v_and_b32_e32 v37, 0xffff0000, v29
	v_lshlrev_b32_e32 v36, 16, v29
	v_and_b32_e32 v29, 0xffff0000, v30
	v_lshlrev_b32_e32 v28, 16, v30
	v_pk_mul_f32 v[32:33], v[46:47], v[32:33] op_sel_hi:[0,1]
	v_pk_mul_f32 v[36:37], v[46:47], v[36:37] op_sel_hi:[0,1]
	v_pk_mul_f32 v[58:59], v[46:47], v[28:29] op_sel_hi:[0,1]
	v_and_b32_e32 v29, 0xffff0000, v31
	v_lshlrev_b32_e32 v28, 16, v31
	v_pk_mul_f32 v[62:63], v[46:47], v[28:29] op_sel_hi:[0,1]
	v_cvt_pk_bf16_f32 v28, v32, v33
	v_cvt_pk_bf16_f32 v29, v36, v37
	v_and_b32_e32 v33, 0xffff0000, v24
	v_lshlrev_b32_e32 v32, 16, v24
	v_and_b32_e32 v37, 0xffff0000, v25
	v_lshlrev_b32_e32 v36, 16, v25
	v_and_b32_e32 v25, 0xffff0000, v26
	v_lshlrev_b32_e32 v24, 16, v26
	v_cvt_pk_bf16_f32 v30, v58, v59
	v_pk_mul_f32 v[32:33], v[46:47], v[32:33] op_sel_hi:[0,1]
	v_pk_mul_f32 v[36:37], v[46:47], v[36:37] op_sel_hi:[0,1]
	v_pk_mul_f32 v[58:59], v[46:47], v[24:25] op_sel_hi:[0,1]
	v_and_b32_e32 v25, 0xffff0000, v27
	v_lshlrev_b32_e32 v24, 16, v27
	v_cvt_pk_bf16_f32 v31, v62, v63
	v_pk_mul_f32 v[62:63], v[46:47], v[24:25] op_sel_hi:[0,1]
	v_cvt_pk_bf16_f32 v24, v32, v33
	v_cvt_pk_bf16_f32 v25, v36, v37
	v_cvt_pk_bf16_f32 v26, v58, v59
	v_cvt_pk_bf16_f32 v27, v62, v63
	global_store_dwordx4 v[48:49], v[28:31], off
	global_store_dwordx4 v[48:49], v[24:27], off offset:16
	v_and_b32_e32 v33, 0xffff0000, v23
	v_and_b32_e32 v31, 0xffff0000, v21
	v_and_or_b32 v24, v53, 8, v55
	v_mul_f32_e32 v25, v80, v56
	v_cvt_pk_bf16_f32 v25, v25, s0
	v_lshl_add_u32 v24, v24, 1, v220
	ds_write_b16 v24, v25
	v_mul_f32_e32 v25, v80, v38
	v_cvt_pk_bf16_f32 v25, v25, s0
	ds_write_b16 v24, v25 offset:1024
	v_mul_f32_e32 v25, v80, v57
	v_cvt_pk_bf16_f32 v25, v25, s0
	ds_write_b16 v24, v25 offset:128
	v_mul_f32_e32 v25, v80, v39
	v_cvt_pk_bf16_f32 v25, v25, s0
	ds_write_b16 v24, v25 offset:1152
	v_mul_f32_e32 v25, v80, v60
	v_cvt_pk_bf16_f32 v25, v25, s0
	ds_write_b16 v24, v25 offset:256
	v_mul_f32_e32 v25, v80, v72
	v_cvt_pk_bf16_f32 v25, v25, s0
	ds_write_b16 v24, v25 offset:1280
	v_mul_f32_e32 v25, v80, v61
	v_cvt_pk_bf16_f32 v25, v25, s0
	ds_write_b16 v24, v25 offset:384
	v_mul_f32_e32 v25, v80, v73
	v_cvt_pk_bf16_f32 v25, v25, s0
	ds_write_b16 v24, v25 offset:1408
	v_mul_f32_e32 v25, v80, v64
	v_cvt_pk_bf16_f32 v25, v25, s0
	ds_write_b16 v24, v25 offset:512
	v_mul_f32_e32 v25, v80, v74
	v_cvt_pk_bf16_f32 v25, v25, s0
	ds_write_b16 v24, v25 offset:1536
	v_mul_f32_e32 v25, v80, v65
	v_cvt_pk_bf16_f32 v25, v25, s0
	ds_write_b16 v24, v25 offset:640
	v_mul_f32_e32 v25, v80, v75
	v_cvt_pk_bf16_f32 v25, v25, s0
	ds_write_b16 v24, v25 offset:1664
	v_mul_f32_e32 v25, v80, v70
	v_cvt_pk_bf16_f32 v25, v25, s0
	ds_write_b16 v24, v25 offset:768
	v_mul_f32_e32 v25, v80, v78
	v_cvt_pk_bf16_f32 v25, v25, s0
	ds_write_b16 v24, v25 offset:1792
	v_mul_f32_e32 v25, v80, v71
	v_cvt_pk_bf16_f32 v25, v25, s0
	ds_write_b16 v24, v25 offset:896
	v_mul_f32_e32 v25, v80, v79
	v_cvt_pk_bf16_f32 v25, v25, s0
	ds_write_b16 v24, v25 offset:1920
	v_mul_f32_e32 v24, 0x3fb8aa3b, v51
	v_exp_f32_e32 v24, v24
	v_sub_f32_e32 v25, v52, v51
	v_mul_f32_e32 v25, 0x3fb8aa3b, v25
	v_lshlrev_b32_e32 v30, 16, v21
	v_and_b32_e32 v29, 0xffff0000, v20
	v_lshlrev_b32_e32 v28, 16, v20
	v_pk_mul_f32 v[20:21], v[24:25], v[30:31] op_sel_hi:[0,1]
	v_and_b32_e32 v31, 0xffff0000, v22
	v_lshlrev_b32_e32 v30, 16, v22
	v_pk_mul_f32 v[28:29], v[24:25], v[28:29] op_sel_hi:[0,1]
	v_pk_mul_f32 v[30:31], v[24:25], v[30:31] op_sel_hi:[0,1]
	v_lshlrev_b32_e32 v32, 16, v23
	v_pk_mul_f32 v[22:23], v[24:25], v[32:33] op_sel_hi:[0,1]
	v_cvt_pk_bf16_f32 v28, v28, v29
	v_cvt_pk_bf16_f32 v29, v20, v21
	v_cvt_pk_bf16_f32 v20, v30, v31
	v_and_b32_e32 v31, 0xffff0000, v17
	v_lshlrev_b32_e32 v30, 16, v17
	v_cvt_pk_bf16_f32 v21, v22, v23
	v_and_b32_e32 v23, 0xffff0000, v16
	v_lshlrev_b32_e32 v22, 16, v16
	v_pk_mul_f32 v[16:17], v[24:25], v[30:31] op_sel_hi:[0,1]
	v_and_b32_e32 v31, 0xffff0000, v18
	v_lshlrev_b32_e32 v30, 16, v18
	v_and_b32_e32 v33, 0xffff0000, v19
	v_lshlrev_b32_e32 v32, 16, v19
	v_pk_mul_f32 v[22:23], v[24:25], v[22:23] op_sel_hi:[0,1]
	v_pk_mul_f32 v[30:31], v[24:25], v[30:31] op_sel_hi:[0,1]
	v_pk_mul_f32 v[18:19], v[24:25], v[32:33] op_sel_hi:[0,1]
	v_cvt_pk_bf16_f32 v22, v22, v23
	v_cvt_pk_bf16_f32 v23, v16, v17
	v_cvt_pk_bf16_f32 v16, v30, v31
	v_cvt_pk_bf16_f32 v17, v18, v19
	global_store_dwordx2 v[68:69], v[28:29], off offset:2048
	global_store_dwordx2 v[68:69], v[20:21], off offset:2064
	global_store_dwordx2 v[68:69], v[22:23], off offset:2080
	global_store_dwordx2 v[68:69], v[16:17], off offset:2096
	v_mul_f32_e64 v28, v47, -v24
	v_and_b32_e32 v19, 0xffff0000, v13
	v_lshlrev_b32_e32 v18, 16, v13
	v_exp_f32_e32 v26, v25
	v_and_b32_e32 v21, 0xffff0000, v12
	v_lshlrev_b32_e32 v20, 16, v12
	v_pk_mul_f32 v[24:25], v[28:29], v[18:19] op_sel_hi:[0,1]
	v_and_b32_e32 v17, 0xffff0000, v14
	v_lshlrev_b32_e32 v16, 16, v14
	v_and_b32_e32 v13, 0xffff0000, v15
	v_lshlrev_b32_e32 v12, 16, v15
	v_pk_mul_f32 v[22:23], v[28:29], v[20:21] op_sel_hi:[0,1]
	v_pk_mul_f32 v[30:31], v[28:29], v[16:17] op_sel_hi:[0,1]
	v_pk_mul_f32 v[14:15], v[28:29], v[12:13] op_sel_hi:[0,1]
	v_cvt_pk_bf16_f32 v33, v24, v25
	v_and_b32_e32 v25, 0xffff0000, v8
	v_lshlrev_b32_e32 v24, 16, v8
	v_cvt_pk_bf16_f32 v32, v22, v23
	v_cvt_pk_bf16_f32 v30, v30, v31
	v_cvt_pk_bf16_f32 v31, v14, v15
	v_pk_mul_f32 v[36:37], v[28:29], v[24:25] op_sel_hi:[0,1]
	v_and_b32_e32 v23, 0xffff0000, v9
	v_lshlrev_b32_e32 v22, 16, v9
	v_and_b32_e32 v15, 0xffff0000, v10
	v_lshlrev_b32_e32 v14, 16, v10
	v_and_b32_e32 v9, 0xffff0000, v11
	v_lshlrev_b32_e32 v8, 16, v11
	v_pk_mul_f32 v[38:39], v[28:29], v[22:23] op_sel_hi:[0,1]
	v_pk_mul_f32 v[48:49], v[28:29], v[14:15] op_sel_hi:[0,1]
	v_pk_mul_f32 v[10:11], v[28:29], v[8:9] op_sel_hi:[0,1]
	v_cvt_pk_bf16_f32 v28, v36, v37
	v_cvt_pk_bf16_f32 v29, v38, v39
	v_cvt_pk_bf16_f32 v36, v48, v49
	v_cvt_pk_bf16_f32 v37, v10, v11
	global_store_dwordx2 v[34:35], v[32:33], off offset:2048
	global_store_dwordx2 v[34:35], v[30:31], off offset:2064
	global_store_dwordx2 v[34:35], v[28:29], off offset:2080
	global_store_dwordx2 v[34:35], v[36:37], off offset:2096
	v_and_b32_e32 v11, 0xffff0000, v0
	v_lshlrev_b32_e32 v10, 16, v0
	v_mov_b32_e32 v28, v47
	v_and_b32_e32 v31, 0xffff0000, v1
	v_lshlrev_b32_e32 v30, 16, v1
	v_and_b32_e32 v1, 0xffff0000, v2
	v_lshlrev_b32_e32 v0, 16, v2
	v_pk_mul_f32 v[10:11], v[28:29], v[10:11] op_sel_hi:[0,1]
	v_pk_mul_f32 v[30:31], v[28:29], v[30:31] op_sel_hi:[0,1]
	v_pk_mul_f32 v[32:33], v[28:29], v[0:1] op_sel_hi:[0,1]
	v_and_b32_e32 v1, 0xffff0000, v3
	v_lshlrev_b32_e32 v0, 16, v3
	v_pk_mul_f32 v[34:35], v[28:29], v[0:1] op_sel_hi:[0,1]
	v_cvt_pk_bf16_f32 v0, v10, v11
	v_cvt_pk_bf16_f32 v1, v30, v31
	v_and_b32_e32 v11, 0xffff0000, v4
	v_lshlrev_b32_e32 v10, 16, v4
	v_and_b32_e32 v31, 0xffff0000, v5
	v_lshlrev_b32_e32 v30, 16, v5
	v_and_b32_e32 v5, 0xffff0000, v6
	v_lshlrev_b32_e32 v4, 16, v6
	v_cvt_pk_bf16_f32 v2, v32, v33
	v_pk_mul_f32 v[10:11], v[28:29], v[10:11] op_sel_hi:[0,1]
	v_pk_mul_f32 v[32:33], v[28:29], v[4:5] op_sel_hi:[0,1]
	v_and_b32_e32 v5, 0xffff0000, v7
	v_lshlrev_b32_e32 v4, 16, v7
	v_pk_mul_f32 v[30:31], v[28:29], v[30:31] op_sel_hi:[0,1]
	v_pk_mul_f32 v[28:29], v[28:29], v[4:5] op_sel_hi:[0,1]
	v_cvt_pk_bf16_f32 v4, v10, v11
	v_lshl_add_u64 v[10:11], v[40:41], 0, s[78:79]
	s_mov_b32 s7, 0x1e000000
	v_add_co_u32_e32 v10, vcc, s7, v10
	v_cvt_pk_bf16_f32 v3, v34, v35
	s_nop 0
	v_addc_co_u32_e32 v11, vcc, 0, v11, vcc
	v_cvt_pk_bf16_f32 v5, v30, v31
	v_cvt_pk_bf16_f32 v6, v32, v33
	v_cvt_pk_bf16_f32 v7, v28, v29
	global_store_dwordx4 v[10:11], v[0:3], off
	global_store_dwordx4 v[10:11], v[4:7], off offset:16
	s_add_u32 s78, s78, 0x1000
	v_add_u32_e32 v0, 16, v53
	v_and_or_b32 v0, v0, 24, v55
	v_mul_f32_e32 v1, v26, v20
	v_cvt_pk_bf16_f32 v1, v1, s0
	v_lshl_add_u32 v0, v0, 1, v220
	ds_write_b16 v0, v1
	v_mul_f32_e32 v1, v26, v24
	v_cvt_pk_bf16_f32 v1, v1, s0
	ds_write_b16 v0, v1 offset:1024
	v_mul_f32_e32 v1, v26, v21
	v_cvt_pk_bf16_f32 v1, v1, s0
	ds_write_b16 v0, v1 offset:128
	v_mul_f32_e32 v1, v26, v25
	v_cvt_pk_bf16_f32 v1, v1, s0
	ds_write_b16 v0, v1 offset:1152
	v_mul_f32_e32 v1, v26, v18
	v_cvt_pk_bf16_f32 v1, v1, s0
	ds_write_b16 v0, v1 offset:256
	v_mul_f32_e32 v1, v26, v22
	v_cvt_pk_bf16_f32 v1, v1, s0
	ds_write_b16 v0, v1 offset:1280
	v_mul_f32_e32 v1, v26, v19
	v_cvt_pk_bf16_f32 v1, v1, s0
	ds_write_b16 v0, v1 offset:384
	v_mul_f32_e32 v1, v26, v23
	v_cvt_pk_bf16_f32 v1, v1, s0
	ds_write_b16 v0, v1 offset:1408
	v_mul_f32_e32 v1, v26, v16
	v_cvt_pk_bf16_f32 v1, v1, s0
	ds_write_b16 v0, v1 offset:512
	v_mul_f32_e32 v1, v26, v14
	v_cvt_pk_bf16_f32 v1, v1, s0
	ds_write_b16 v0, v1 offset:1536
	v_mul_f32_e32 v1, v26, v17
	v_cvt_pk_bf16_f32 v1, v1, s0
	ds_write_b16 v0, v1 offset:640
	v_mul_f32_e32 v1, v26, v15
	v_cvt_pk_bf16_f32 v1, v1, s0
	ds_write_b16 v0, v1 offset:1664
	v_mul_f32_e32 v1, v26, v12
	v_cvt_pk_bf16_f32 v1, v1, s0
	ds_write_b16 v0, v1 offset:768
	v_mul_f32_e32 v1, v26, v8
	v_cvt_pk_bf16_f32 v1, v1, s0
	ds_write_b16 v0, v1 offset:1792
	v_mul_f32_e32 v1, v26, v13
	v_cvt_pk_bf16_f32 v1, v1, s0
	ds_write_b16 v0, v1 offset:896
	v_mul_f32_e32 v1, v26, v9
	s_addc_u32 s79, s79, 0
	s_add_i32 s6, s6, 4
	s_add_i32 s3, s3, 16
	v_cvt_pk_bf16_f32 v1, v1, s0
	v_add_u32_e32 v53, 32, v53
	s_cmpk_eq_i32 s78, 0x4000
	ds_write_b16 v0, v1 offset:1920
	s_cbranch_scc0 .LBB0_647
	v_lshl_add_u64 v[0:1], v[134:135], 0, s[0:1]
	s_mov_b32 s0, 0

.LBB0_732:
	s_add_i32 s0, s83, -1
	s_cmp_lt_i32 s0, s77
	s_cselect_b64 s[4:5], -1, 0
	s_cmp_ge_i32 s0, s77
	v_add_u32_e32 v225, s84, v138
	v_lshl_add_u64 v[198:199], s[78:79], 0, v[186:187]
	v_lshl_add_u64 v[196:197], s[78:79], 0, v[188:189]
	v_lshl_add_u64 v[194:195], s[78:79], 0, v[190:191]
	s_cbranch_scc1 .LBB0_734
	v_add_u32_e32 v66, 64, v225
	v_ashrrev_i32_e32 v67, 31, v66
	v_add_u32_e32 v68, 0x60, v225
	v_lshlrev_b64 v[66:67], 8, v[66:67]
	v_ashrrev_i32_e32 v69, 31, v68
	v_lshl_add_u64 v[66:67], v[192:193], 0, v[66:67]
	v_lshlrev_b64 v[68:69], 8, v[68:69]
	v_lshl_add_u64 v[68:69], v[192:193], 0, v[68:69]
	v_mov_b32_e32 v242, v66
	v_mov_b32_e32 v243, v67
	v_mov_b32_e32 v244, v68
	v_mov_b32_e32 v245, v69
	v_add_co_u32_e32 v66, vcc, 0x17006000, v198
	s_nop 1
	v_addc_co_u32_e32 v67, vcc, 0, v199, vcc
	v_add_co_u32_e32 v68, vcc, 0x17006000, v196
	s_nop 1
	v_addc_co_u32_e32 v69, vcc, 0, v197, vcc
	v_mov_b32_e32 v246, v66
	v_mov_b32_e32 v247, v67
	v_mov_b32_e32 v248, v68
	v_mov_b32_e32 v249, v69
	v_add_co_u32_e32 v66, vcc, 0x17006000, v194
	s_nop 1
	v_addc_co_u32_e32 v67, vcc, 0, v195, vcc
	v_mov_b32_e32 v250, v66
	v_mov_b32_e32 v251, v67
.LBB0_734:
	s_add_i32 s0, s82, 32
	s_cmp_ge_i32 s84, s0
	s_cbranch_scc1 .Lattn_skip1
	s_and_b64 vcc, exec, s[4:5]
	s_cbranch_vccnz .Lattn_qk1_pf
	ds_read_b128 v[194:197], v139 offset:32768
	ds_read_b128 v[226:229], v139 offset:45056
	ds_read_b128 v[234:237], v202 offset:32768
	ds_read_b128 v[230:233], v220
	ds_read_b128 v[238:241], v220 offset:1024
	s_add_i32 s0, s84, 63
	s_cmp_le_i32 s0, s82
	s_waitcnt lgkmcnt(4)
	v_mfma_f32_32x32x16_bf16 v[82:97], v[194:197], v[98:101], 0
	ds_read_b128 v[194:197], v202 offset:45056
	s_waitcnt lgkmcnt(4)
	v_mfma_f32_32x32x16_bf16 v[66:81], v[226:229], v[98:101], 0
	ds_read_b128 v[226:229], v203 offset:32768
	s_waitcnt lgkmcnt(4)
	v_mfma_f32_32x32x16_bf16 v[82:97], v[234:237], v[102:105], v[82:97]
	ds_read_b128 v[234:237], v203 offset:45056
	s_waitcnt lgkmcnt(2)
	v_mfma_f32_32x32x16_bf16 v[66:81], v[194:197], v[102:105], v[66:81]
	ds_read_b128 v[194:197], v204 offset:32768
	s_waitcnt lgkmcnt(2)
	v_mfma_f32_32x32x16_bf16 v[82:97], v[226:229], v[106:109], v[82:97]
	ds_read_b128 v[226:229], v204 offset:45056
	s_waitcnt lgkmcnt(2)
	v_mfma_f32_32x32x16_bf16 v[66:81], v[234:237], v[106:109], v[66:81]
	ds_read_b128 v[234:237], v139 offset:32896
	s_waitcnt lgkmcnt(2)
	v_mfma_f32_32x32x16_bf16 v[82:97], v[194:197], v[110:113], v[82:97]
	ds_read_b128 v[194:197], v139 offset:45184
	s_waitcnt lgkmcnt(2)
	v_mfma_f32_32x32x16_bf16 v[66:81], v[226:229], v[110:113], v[66:81]
	ds_read_b128 v[226:229], v202 offset:32896
	s_waitcnt lgkmcnt(2)
	v_mfma_f32_32x32x16_bf16 v[82:97], v[234:237], v[230:233], v[82:97]
	ds_read_b128 v[234:237], v202 offset:45184
	s_waitcnt lgkmcnt(2)
	v_mfma_f32_32x32x16_bf16 v[66:81], v[194:197], v[230:233], v[66:81]
	ds_read_b128 v[194:197], v203 offset:32896
	ds_read_b128 v[230:233], v220 offset:2048
	s_waitcnt lgkmcnt(3)
	v_mfma_f32_32x32x16_bf16 v[82:97], v[226:229], v[238:241], v[82:97]
	ds_read_b128 v[226:229], v203 offset:45184
	s_waitcnt lgkmcnt(3)
	v_mfma_f32_32x32x16_bf16 v[66:81], v[234:237], v[238:241], v[66:81]
	ds_read_b128 v[234:237], v204 offset:32896
	ds_read_b128 v[238:241], v220 offset:3072
	s_waitcnt lgkmcnt(3)
	v_mfma_f32_32x32x16_bf16 v[82:97], v[194:197], v[230:233], v[82:97]
	ds_read_b128 v[194:197], v204 offset:45184
	s_waitcnt lgkmcnt(3)
	v_mfma_f32_32x32x16_bf16 v[66:81], v[226:229], v[230:233], v[66:81]
	ds_read_b128 v[226:229], v139 offset:33024
	ds_read_b128 v[230:233], v220 offset:4096
	s_waitcnt lgkmcnt(3)
	v_mfma_f32_32x32x16_bf16 v[82:97], v[234:237], v[238:241], v[82:97]
	ds_read_b128 v[234:237], v139 offset:45312
	s_waitcnt lgkmcnt(3)
	v_mfma_f32_32x32x16_bf16 v[66:81], v[194:197], v[238:241], v[66:81]
	ds_read_b128 v[194:197], v202 offset:33024
	ds_read_b128 v[238:241], v220 offset:5120
	s_waitcnt lgkmcnt(3)
	v_mfma_f32_32x32x16_bf16 v[82:97], v[226:229], v[230:233], v[82:97]
	ds_read_b128 v[226:229], v202 offset:45312
	s_waitcnt lgkmcnt(3)
	v_mfma_f32_32x32x16_bf16 v[66:81], v[234:237], v[230:233], v[66:81]
	ds_read_b128 v[234:237], v203 offset:33024
	ds_read_b128 v[230:233], v220 offset:6144
	s_waitcnt lgkmcnt(3)
	v_mfma_f32_32x32x16_bf16 v[82:97], v[194:197], v[238:241], v[82:97]
	ds_read_b128 v[194:197], v203 offset:45312
	s_waitcnt lgkmcnt(3)
	v_mfma_f32_32x32x16_bf16 v[66:81], v[226:229], v[238:241], v[66:81]
	ds_read_b128 v[226:229], v204 offset:33024
	ds_read_b128 v[238:241], v220 offset:7168
	s_waitcnt lgkmcnt(3)
	v_mfma_f32_32x32x16_bf16 v[82:97], v[234:237], v[230:233], v[82:97]
	ds_read_b128 v[234:237], v204 offset:45312
	s_waitcnt lgkmcnt(3)
	v_mfma_f32_32x32x16_bf16 v[66:81], v[194:197], v[230:233], v[66:81]
	s_waitcnt lgkmcnt(1)
	v_mfma_f32_32x32x16_bf16 v[82:97], v[226:229], v[238:241], v[82:97]
	s_waitcnt lgkmcnt(0)
	v_mfma_f32_32x32x16_bf16 v[66:81], v[234:237], v[238:241], v[66:81]
	s_nop 1
	s_cbranch_scc1 .LBB0_736
.Lattn_b135:
	v_cmp_gt_i32_e64 s[70:71], 26, v221
	v_cmp_gt_i32_e64 s[72:73], 27, v221
	v_cmp_gt_i32_e64 s[68:69], 25, v221
	s_and_b64 s[70:71], s[72:73], s[70:71]
	v_cmp_gt_i32_e64 s[66:67], 24, v221
	s_and_b64 s[68:69], s[70:71], s[68:69]
	v_cmp_gt_i32_e64 s[64:65], 19, v221
	s_and_b64 s[66:67], s[68:69], s[66:67]
	v_cmp_gt_i32_e64 s[62:63], 18, v221
	s_and_b64 s[64:65], s[66:67], s[64:65]
	v_cmp_gt_i32_e64 s[56:57], 17, v221
	s_and_b64 s[62:63], s[64:65], s[62:63]
	v_cmp_gt_i32_e64 s[54:55], 16, v221
	s_and_b64 s[56:57], s[62:63], s[56:57]
	v_cmp_gt_i32_e64 s[52:53], 11, v221
	s_and_b64 s[54:55], s[56:57], s[54:55]
	v_cmp_gt_i32_e64 s[50:51], 10, v221
	s_and_b64 s[52:53], s[54:55], s[52:53]
	v_cmp_gt_i32_e64 s[48:49], 9, v221
	s_and_b64 s[50:51], s[52:53], s[50:51]
	v_cmp_gt_i32_e64 s[46:47], 8, v221
	s_and_b64 s[48:49], s[50:51], s[48:49]
	v_cmp_gt_i32_e64 s[44:45], 3, v221
	s_and_b64 s[46:47], s[48:49], s[46:47]
	v_cmp_gt_i32_e64 s[42:43], 2, v221
	s_and_b64 s[44:45], s[46:47], s[44:45]
	v_cmp_gt_i32_e64 s[40:41], 1, v221
	s_and_b64 s[42:43], s[44:45], s[42:43]
	v_cmp_gt_i32_e64 s[38:39], 0, v221
	s_and_b64 s[40:41], s[42:43], s[40:41]
	s_and_b64 s[38:39], s[40:41], s[38:39]
	v_cmp_gt_i32_e64 s[36:37], 58, v221
	v_cndmask_b32_e64 v82, v82, v216, s[38:39]
	v_cmp_gt_i32_e64 s[38:39], 59, v221
	v_cmp_gt_i32_e64 s[34:35], 57, v221
	s_and_b64 s[36:37], s[38:39], s[36:37]
	v_cmp_gt_i32_e64 s[0:1], 56, v221
	s_and_b64 s[34:35], s[36:37], s[34:35]
	v_cmp_gt_i32_e64 s[30:31], 51, v221
	s_and_b64 s[0:1], s[34:35], s[0:1]
	v_cmp_gt_i32_e64 s[28:29], 50, v221
	v_cndmask_b32_e64 v78, v78, v216, s[0:1]
	s_and_b64 s[0:1], s[0:1], s[30:31]
	v_cmp_gt_i32_e64 s[26:27], 49, v221
	v_cndmask_b32_e64 v77, v77, v216, s[0:1]
	s_and_b64 s[0:1], s[0:1], s[28:29]
	v_cmp_gt_i32_e64 s[24:25], 48, v221
	v_cndmask_b32_e64 v76, v76, v216, s[0:1]
	s_and_b64 s[0:1], s[0:1], s[26:27]
	v_cmp_gt_i32_e64 s[22:23], 43, v221
	v_cndmask_b32_e64 v75, v75, v216, s[0:1]
	s_and_b64 s[0:1], s[0:1], s[24:25]
	v_cmp_gt_i32_e64 s[20:21], 42, v221
	v_cndmask_b32_e64 v74, v74, v216, s[0:1]
	s_and_b64 s[0:1], s[0:1], s[22:23]
	v_cmp_gt_i32_e64 s[18:19], 41, v221
	v_cndmask_b32_e64 v73, v73, v216, s[0:1]
	s_and_b64 s[0:1], s[0:1], s[20:21]
	v_cmp_gt_i32_e64 s[16:17], 40, v221
	v_cndmask_b32_e64 v72, v72, v216, s[0:1]
	s_and_b64 s[0:1], s[0:1], s[18:19]
	v_cmp_gt_i32_e64 s[14:15], 35, v221
	v_cndmask_b32_e64 v71, v71, v216, s[0:1]
	s_and_b64 s[0:1], s[0:1], s[16:17]
	v_cmp_gt_i32_e64 s[12:13], 34, v221
	v_cndmask_b32_e64 v70, v70, v216, s[0:1]
	s_and_b64 s[0:1], s[0:1], s[14:15]
	v_cmp_gt_i32_e64 s[10:11], 33, v221
	v_cndmask_b32_e64 v69, v69, v216, s[0:1]
	s_and_b64 s[0:1], s[0:1], s[12:13]
	v_cmp_gt_i32_e32 vcc, 32, v221
	v_cndmask_b32_e64 v68, v68, v216, s[0:1]
	s_and_b64 s[0:1], s[0:1], s[10:11]
	s_and_b64 vcc, s[0:1], vcc
	v_cndmask_b32_e64 v97, v97, v216, s[72:73]
	v_cndmask_b32_e64 v96, v96, v216, s[70:71]
	v_cndmask_b32_e64 v95, v95, v216, s[68:69]
	v_cndmask_b32_e64 v94, v94, v216, s[66:67]
	v_cndmask_b32_e64 v93, v93, v216, s[64:65]
	v_cndmask_b32_e64 v92, v92, v216, s[62:63]
	v_cndmask_b32_e64 v91, v91, v216, s[56:57]
	v_cndmask_b32_e64 v90, v90, v216, s[54:55]
	v_cndmask_b32_e64 v89, v89, v216, s[52:53]
	v_cndmask_b32_e64 v88, v88, v216, s[50:51]
	v_cndmask_b32_e64 v87, v87, v216, s[48:49]
	v_cndmask_b32_e64 v86, v86, v216, s[46:47]
	v_cndmask_b32_e64 v85, v85, v216, s[44:45]
	v_cndmask_b32_e64 v84, v84, v216, s[42:43]
	v_cndmask_b32_e64 v83, v83, v216, s[40:41]
	v_cndmask_b32_e64 v81, v81, v216, s[38:39]
	v_cndmask_b32_e64 v80, v80, v216, s[36:37]
	v_cndmask_b32_e64 v79, v79, v216, s[34:35]
	v_cndmask_b32_e64 v67, v67, v216, s[0:1]
	v_cndmask_b32_e32 v66, v66, v216, vcc

.LBB0_742:
	s_cmp_lt_i32 s83, s77
	s_cselect_b64 s[94:95], -1, 0
	s_cmp_ge_i32 s83, s77
	s_cselect_b64 s[4:5], -1, 0
	s_and_b64 vcc, exec, s[4:5]
	s_waitcnt lgkmcnt(0)
	s_barrier
	s_cbranch_vccnz .LBB0_744
	v_add_u32_e32 v66, 0x80, v225
	v_ashrrev_i32_e32 v67, 31, v66
	v_add_u32_e32 v68, 0xa0, v225
	v_lshlrev_b64 v[66:67], 8, v[66:67]
	v_ashrrev_i32_e32 v69, 31, v68
	v_lshl_add_u64 v[66:67], v[192:193], 0, v[66:67]
	v_lshlrev_b64 v[68:69], 8, v[68:69]
	v_lshl_add_u64 v[68:69], v[192:193], 0, v[68:69]
	v_mov_b32_e32 v242, v66
	v_mov_b32_e32 v243, v67
	v_mov_b32_e32 v244, v68
	v_mov_b32_e32 v245, v69
	v_lshl_add_u64 v[66:67], s[78:79], 0, v[186:187]
	v_lshl_add_u64 v[68:69], s[78:79], 0, v[188:189]
	v_add_co_u32_e32 v66, vcc, 0x1700c000, v66
	s_nop 1
	v_addc_co_u32_e32 v67, vcc, 0, v67, vcc
	v_add_co_u32_e32 v68, vcc, 0x1700c000, v68
	s_nop 1
	v_addc_co_u32_e32 v69, vcc, 0, v69, vcc
	v_mov_b32_e32 v246, v66
	v_mov_b32_e32 v247, v67
	v_mov_b32_e32 v248, v68
	v_mov_b32_e32 v249, v69
	v_lshl_add_u64 v[66:67], s[78:79], 0, v[190:191]
	v_add_co_u32_e32 v66, vcc, 0x1700c000, v66
	s_nop 1
	v_addc_co_u32_e32 v67, vcc, 0, v67, vcc
	v_mov_b32_e32 v250, v66
	v_mov_b32_e32 v251, v67
.LBB0_744:
	s_add_i32 s0, s84, 32
	s_cmp_ge_i32 s0, s82
	s_cbranch_scc1 .Lattn_skip2
	s_and_b64 vcc, exec, s[94:95]
	s_cbranch_vccnz .Lattn_qk2_pf
	ds_read_b128 v[194:197], v139 offset:57344
	ds_read_b128 v[226:229], v205 offset:12288
	ds_read_b128 v[234:237], v202 offset:57344
	ds_read_b128 v[230:233], v220
	ds_read_b128 v[238:241], v220 offset:1024
	s_add_i32 s0, s84, 0x7f
	s_cmp_le_i32 s0, s82
	s_waitcnt lgkmcnt(4)
	v_mfma_f32_32x32x16_bf16 v[82:97], v[194:197], v[98:101], 0
	ds_read_b128 v[194:197], v206 offset:12288
	s_waitcnt lgkmcnt(4)
	v_mfma_f32_32x32x16_bf16 v[66:81], v[226:229], v[98:101], 0
	ds_read_b128 v[226:229], v203 offset:57344
	s_waitcnt lgkmcnt(4)
	v_mfma_f32_32x32x16_bf16 v[82:97], v[234:237], v[102:105], v[82:97]
	ds_read_b128 v[234:237], v207 offset:12288
	s_waitcnt lgkmcnt(2)
	v_mfma_f32_32x32x16_bf16 v[66:81], v[194:197], v[102:105], v[66:81]
	ds_read_b128 v[194:197], v204 offset:57344
	s_waitcnt lgkmcnt(2)
	v_mfma_f32_32x32x16_bf16 v[82:97], v[226:229], v[106:109], v[82:97]
	ds_read_b128 v[226:229], v208 offset:12288
	s_waitcnt lgkmcnt(2)
	v_mfma_f32_32x32x16_bf16 v[66:81], v[234:237], v[106:109], v[66:81]
	ds_read_b128 v[234:237], v139 offset:57472
	s_waitcnt lgkmcnt(2)
	v_mfma_f32_32x32x16_bf16 v[82:97], v[194:197], v[110:113], v[82:97]
	ds_read_b128 v[194:197], v205 offset:12416
	s_waitcnt lgkmcnt(2)
	v_mfma_f32_32x32x16_bf16 v[66:81], v[226:229], v[110:113], v[66:81]
	ds_read_b128 v[226:229], v202 offset:57472
	s_waitcnt lgkmcnt(2)
	v_mfma_f32_32x32x16_bf16 v[82:97], v[234:237], v[230:233], v[82:97]
	ds_read_b128 v[234:237], v206 offset:12416
	s_waitcnt lgkmcnt(2)
	v_mfma_f32_32x32x16_bf16 v[66:81], v[194:197], v[230:233], v[66:81]
	ds_read_b128 v[194:197], v203 offset:57472
	ds_read_b128 v[230:233], v220 offset:2048
	s_waitcnt lgkmcnt(3)
	v_mfma_f32_32x32x16_bf16 v[82:97], v[226:229], v[238:241], v[82:97]
	ds_read_b128 v[226:229], v207 offset:12416
	s_waitcnt lgkmcnt(3)
	v_mfma_f32_32x32x16_bf16 v[66:81], v[234:237], v[238:241], v[66:81]
	ds_read_b128 v[234:237], v204 offset:57472
	ds_read_b128 v[238:241], v220 offset:3072
	s_waitcnt lgkmcnt(3)
	v_mfma_f32_32x32x16_bf16 v[82:97], v[194:197], v[230:233], v[82:97]
	ds_read_b128 v[194:197], v208 offset:12416
	s_waitcnt lgkmcnt(3)
	v_mfma_f32_32x32x16_bf16 v[66:81], v[226:229], v[230:233], v[66:81]
	ds_read_b128 v[226:229], v139 offset:57600
	ds_read_b128 v[230:233], v220 offset:4096
	s_waitcnt lgkmcnt(3)
	v_mfma_f32_32x32x16_bf16 v[82:97], v[234:237], v[238:241], v[82:97]
	ds_read_b128 v[234:237], v205 offset:12544
	s_waitcnt lgkmcnt(3)
	v_mfma_f32_32x32x16_bf16 v[66:81], v[194:197], v[238:241], v[66:81]
	ds_read_b128 v[194:197], v202 offset:57600
	ds_read_b128 v[238:241], v220 offset:5120
	s_waitcnt lgkmcnt(3)
	v_mfma_f32_32x32x16_bf16 v[82:97], v[226:229], v[230:233], v[82:97]
	ds_read_b128 v[226:229], v206 offset:12544
	s_waitcnt lgkmcnt(3)
	v_mfma_f32_32x32x16_bf16 v[66:81], v[234:237], v[230:233], v[66:81]
	ds_read_b128 v[234:237], v203 offset:57600
	ds_read_b128 v[230:233], v220 offset:6144
	s_waitcnt lgkmcnt(3)
	v_mfma_f32_32x32x16_bf16 v[82:97], v[194:197], v[238:241], v[82:97]
	ds_read_b128 v[194:197], v207 offset:12544
	s_waitcnt lgkmcnt(3)
	v_mfma_f32_32x32x16_bf16 v[66:81], v[226:229], v[238:241], v[66:81]
	ds_read_b128 v[226:229], v204 offset:57600
	ds_read_b128 v[238:241], v220 offset:7168
	s_waitcnt lgkmcnt(3)
	v_mfma_f32_32x32x16_bf16 v[82:97], v[234:237], v[230:233], v[82:97]
	ds_read_b128 v[234:237], v208 offset:12544
	s_waitcnt lgkmcnt(3)
	v_mfma_f32_32x32x16_bf16 v[66:81], v[194:197], v[230:233], v[66:81]
	s_waitcnt lgkmcnt(1)
	v_mfma_f32_32x32x16_bf16 v[82:97], v[226:229], v[238:241], v[82:97]
	s_waitcnt lgkmcnt(0)
	v_mfma_f32_32x32x16_bf16 v[66:81], v[234:237], v[238:241], v[66:81]
	s_nop 1
	s_cbranch_scc1 .LBB0_746
.Lattn_b235:
	v_subrev_u32_e32 v194, 64, v221
	v_cmp_gt_i32_e64 s[70:71], 26, v194
	v_cmp_gt_i32_e64 s[72:73], 27, v194
	v_cmp_gt_i32_e64 s[68:69], 25, v194
	s_and_b64 s[70:71], s[72:73], s[70:71]
	v_cmp_gt_i32_e64 s[66:67], 24, v194
	s_and_b64 s[68:69], s[70:71], s[68:69]
	v_cmp_gt_i32_e64 s[64:65], 19, v194
	s_and_b64 s[66:67], s[68:69], s[66:67]
	v_cmp_gt_i32_e64 s[62:63], 18, v194
	s_and_b64 s[64:65], s[66:67], s[64:65]
	v_cmp_gt_i32_e64 s[56:57], 17, v194
	s_and_b64 s[62:63], s[64:65], s[62:63]
	v_cmp_gt_i32_e64 s[54:55], 16, v194
	s_and_b64 s[56:57], s[62:63], s[56:57]
	v_cmp_gt_i32_e64 s[52:53], 11, v194
	s_and_b64 s[54:55], s[56:57], s[54:55]
	v_cmp_gt_i32_e64 s[50:51], 10, v194
	s_and_b64 s[52:53], s[54:55], s[52:53]
	v_cmp_gt_i32_e64 s[48:49], 9, v194
	s_and_b64 s[50:51], s[52:53], s[50:51]
	v_cmp_gt_i32_e64 s[46:47], 8, v194
	s_and_b64 s[48:49], s[50:51], s[48:49]
	v_cmp_gt_i32_e64 s[44:45], 3, v194
	s_and_b64 s[46:47], s[48:49], s[46:47]
	v_cmp_gt_i32_e64 s[42:43], 2, v194
	s_and_b64 s[44:45], s[46:47], s[44:45]
	v_cmp_gt_i32_e64 s[40:41], 1, v194
	s_and_b64 s[42:43], s[44:45], s[42:43]
	v_cmp_gt_i32_e64 s[38:39], 0, v194
	s_and_b64 s[40:41], s[42:43], s[40:41]
	s_and_b64 s[38:39], s[40:41], s[38:39]
	v_cmp_gt_i32_e64 s[36:37], 58, v194
	v_cndmask_b32_e64 v82, v82, v216, s[38:39]
	v_cmp_gt_i32_e64 s[38:39], 59, v194
	v_cmp_gt_i32_e64 s[34:35], 57, v194
	s_and_b64 s[36:37], s[38:39], s[36:37]
	v_cmp_gt_i32_e64 s[0:1], 56, v194
	s_and_b64 s[34:35], s[36:37], s[34:35]
	v_cmp_gt_i32_e64 s[30:31], 51, v194
	s_and_b64 s[0:1], s[34:35], s[0:1]
	v_cmp_gt_i32_e64 s[28:29], 50, v194
	v_cndmask_b32_e64 v78, v78, v216, s[0:1]
	s_and_b64 s[0:1], s[0:1], s[30:31]
	v_cmp_gt_i32_e64 s[26:27], 49, v194
	v_cndmask_b32_e64 v77, v77, v216, s[0:1]
	s_and_b64 s[0:1], s[0:1], s[28:29]
	v_cmp_gt_i32_e64 s[24:25], 48, v194
	v_cndmask_b32_e64 v76, v76, v216, s[0:1]
	s_and_b64 s[0:1], s[0:1], s[26:27]
	v_cmp_gt_i32_e64 s[22:23], 43, v194
	v_cndmask_b32_e64 v75, v75, v216, s[0:1]
	s_and_b64 s[0:1], s[0:1], s[24:25]
	v_cmp_gt_i32_e64 s[20:21], 42, v194
	v_cndmask_b32_e64 v74, v74, v216, s[0:1]
	s_and_b64 s[0:1], s[0:1], s[22:23]
	v_cmp_gt_i32_e64 s[18:19], 41, v194
	v_cndmask_b32_e64 v73, v73, v216, s[0:1]
	s_and_b64 s[0:1], s[0:1], s[20:21]
	v_cmp_gt_i32_e64 s[16:17], 40, v194
	v_cndmask_b32_e64 v72, v72, v216, s[0:1]
	s_and_b64 s[0:1], s[0:1], s[18:19]
	v_cmp_gt_i32_e64 s[14:15], 35, v194
	v_cndmask_b32_e64 v71, v71, v216, s[0:1]
	s_and_b64 s[0:1], s[0:1], s[16:17]
	v_cmp_gt_i32_e64 s[12:13], 34, v194
	v_cndmask_b32_e64 v70, v70, v216, s[0:1]
	s_and_b64 s[0:1], s[0:1], s[14:15]
	v_cmp_gt_i32_e64 s[10:11], 33, v194
	v_cndmask_b32_e64 v69, v69, v216, s[0:1]
	s_and_b64 s[0:1], s[0:1], s[12:13]
	v_cmp_gt_i32_e32 vcc, 32, v194
	v_cndmask_b32_e64 v68, v68, v216, s[0:1]
	s_and_b64 s[0:1], s[0:1], s[10:11]
	s_and_b64 vcc, s[0:1], vcc
	v_cndmask_b32_e64 v97, v97, v216, s[72:73]
	v_cndmask_b32_e64 v96, v96, v216, s[70:71]
	v_cndmask_b32_e64 v95, v95, v216, s[68:69]
	v_cndmask_b32_e64 v94, v94, v216, s[66:67]
	v_cndmask_b32_e64 v93, v93, v216, s[64:65]
	v_cndmask_b32_e64 v92, v92, v216, s[62:63]
	v_cndmask_b32_e64 v91, v91, v216, s[56:57]
	v_cndmask_b32_e64 v90, v90, v216, s[54:55]
	v_cndmask_b32_e64 v89, v89, v216, s[52:53]
	v_cndmask_b32_e64 v88, v88, v216, s[50:51]
	v_cndmask_b32_e64 v87, v87, v216, s[48:49]
	v_cndmask_b32_e64 v86, v86, v216, s[46:47]
	v_cndmask_b32_e64 v85, v85, v216, s[44:45]
	v_cndmask_b32_e64 v84, v84, v216, s[42:43]
	v_cndmask_b32_e64 v83, v83, v216, s[40:41]
	v_cndmask_b32_e64 v81, v81, v216, s[38:39]
	v_cndmask_b32_e64 v80, v80, v216, s[36:37]
	v_cndmask_b32_e64 v79, v79, v216, s[34:35]
	v_cndmask_b32_e64 v67, v67, v216, s[0:1]
	v_cndmask_b32_e32 v66, v66, v216, vcc

.Lattn_skip1:
	v_mov_b32_e32 v0, 1.0
	v_mov_b32_e32 v222, 0
	v_mov_b32_e32 v223, 0
	s_andn2_b64 vcc, exec, s[4:5]
	s_cbranch_vccnz .LBB0_742
	global_load_dwordx4 v[114:117], v[242:243], off
	global_load_dwordx4 v[118:121], v[244:245], off
	global_load_dwordx4 v[122:125], v[246:247], off
	global_load_dwordx4 v[126:129], v[248:249], off
	global_load_dwordx4 v[130:133], v[250:251], off
	s_branch .Lattn_stage1
.Lattn_skip2:
	v_mov_b32_e32 v194, 1.0
	v_mov_b32_e32 v66, 0
	v_mov_b32_e32 v67, 0
	s_mov_b32 s70, s80
	s_mov_b32 s71, s81
	s_mov_b64 s[72:73], s[86:87]
	s_andn2_b64 vcc, exec, s[94:95]
	s_cbranch_vccnz .LBB0_731
	global_load_dwordx4 v[114:117], v[242:243], off
	global_load_dwordx4 v[118:121], v[244:245], off
	global_load_dwordx4 v[122:125], v[246:247], off
	global_load_dwordx4 v[126:129], v[248:249], off
	global_load_dwordx4 v[130:133], v[250:251], off
	s_branch .Lattn_stage2
.Lattn_qk1_pf:
	ds_read_b128 v[194:197], v139 offset:32768
	ds_read_b128 v[226:229], v139 offset:45056
	ds_read_b128 v[234:237], v202 offset:32768
	ds_read_b128 v[230:233], v220
	ds_read_b128 v[238:241], v220 offset:1024
	s_add_i32 s0, s84, 63
	s_cmp_le_i32 s0, s82
	s_waitcnt lgkmcnt(4)
	v_mfma_f32_32x32x16_bf16 v[82:97], v[194:197], v[98:101], 0
	ds_read_b128 v[194:197], v202 offset:45056
	s_waitcnt lgkmcnt(4)
	v_mfma_f32_32x32x16_bf16 v[66:81], v[226:229], v[98:101], 0
	global_load_dwordx4 v[114:117], v[242:243], off
	ds_read_b128 v[226:229], v203 offset:32768
	s_waitcnt lgkmcnt(4)
	v_mfma_f32_32x32x16_bf16 v[82:97], v[234:237], v[102:105], v[82:97]
	ds_read_b128 v[234:237], v203 offset:45056
	s_waitcnt lgkmcnt(2)
	v_mfma_f32_32x32x16_bf16 v[66:81], v[194:197], v[102:105], v[66:81]
	global_load_dwordx4 v[118:121], v[244:245], off
	ds_read_b128 v[194:197], v204 offset:32768
	s_waitcnt lgkmcnt(2)
	v_mfma_f32_32x32x16_bf16 v[82:97], v[226:229], v[106:109], v[82:97]
	ds_read_b128 v[226:229], v204 offset:45056
	s_waitcnt lgkmcnt(2)
	v_mfma_f32_32x32x16_bf16 v[66:81], v[234:237], v[106:109], v[66:81]
	global_load_dwordx4 v[122:125], v[246:247], off
	ds_read_b128 v[234:237], v139 offset:32896
	s_waitcnt lgkmcnt(2)
	v_mfma_f32_32x32x16_bf16 v[82:97], v[194:197], v[110:113], v[82:97]
	ds_read_b128 v[194:197], v139 offset:45184
	s_waitcnt lgkmcnt(2)
	v_mfma_f32_32x32x16_bf16 v[66:81], v[226:229], v[110:113], v[66:81]
	global_load_dwordx4 v[126:129], v[248:249], off
	ds_read_b128 v[226:229], v202 offset:32896
	s_waitcnt lgkmcnt(2)
	v_mfma_f32_32x32x16_bf16 v[82:97], v[234:237], v[230:233], v[82:97]
	ds_read_b128 v[234:237], v202 offset:45184
	s_waitcnt lgkmcnt(2)
	v_mfma_f32_32x32x16_bf16 v[66:81], v[194:197], v[230:233], v[66:81]
	global_load_dwordx4 v[130:133], v[250:251], off
	ds_read_b128 v[194:197], v203 offset:32896
	ds_read_b128 v[230:233], v220 offset:2048
	s_waitcnt lgkmcnt(3)
	v_mfma_f32_32x32x16_bf16 v[82:97], v[226:229], v[238:241], v[82:97]
	ds_read_b128 v[226:229], v203 offset:45184
	s_waitcnt lgkmcnt(3)
	v_mfma_f32_32x32x16_bf16 v[66:81], v[234:237], v[238:241], v[66:81]
	ds_read_b128 v[234:237], v204 offset:32896
	ds_read_b128 v[238:241], v220 offset:3072
	s_waitcnt lgkmcnt(3)
	v_mfma_f32_32x32x16_bf16 v[82:97], v[194:197], v[230:233], v[82:97]
	ds_read_b128 v[194:197], v204 offset:45184
	s_waitcnt lgkmcnt(3)
	v_mfma_f32_32x32x16_bf16 v[66:81], v[226:229], v[230:233], v[66:81]
	ds_read_b128 v[226:229], v139 offset:33024
	ds_read_b128 v[230:233], v220 offset:4096
	s_waitcnt lgkmcnt(3)
	v_mfma_f32_32x32x16_bf16 v[82:97], v[234:237], v[238:241], v[82:97]
	ds_read_b128 v[234:237], v139 offset:45312
	s_waitcnt lgkmcnt(3)
	v_mfma_f32_32x32x16_bf16 v[66:81], v[194:197], v[238:241], v[66:81]
	ds_read_b128 v[194:197], v202 offset:33024
	ds_read_b128 v[238:241], v220 offset:5120
	s_waitcnt lgkmcnt(3)
	v_mfma_f32_32x32x16_bf16 v[82:97], v[226:229], v[230:233], v[82:97]
	ds_read_b128 v[226:229], v202 offset:45312
	s_waitcnt lgkmcnt(3)
	v_mfma_f32_32x32x16_bf16 v[66:81], v[234:237], v[230:233], v[66:81]
	ds_read_b128 v[234:237], v203 offset:33024
	ds_read_b128 v[230:233], v220 offset:6144
	s_waitcnt lgkmcnt(3)
	v_mfma_f32_32x32x16_bf16 v[82:97], v[194:197], v[238:241], v[82:97]
	ds_read_b128 v[194:197], v203 offset:45312
	s_waitcnt lgkmcnt(3)
	v_mfma_f32_32x32x16_bf16 v[66:81], v[226:229], v[238:241], v[66:81]
	ds_read_b128 v[226:229], v204 offset:33024
	ds_read_b128 v[238:241], v220 offset:7168
	s_waitcnt lgkmcnt(3)
	v_mfma_f32_32x32x16_bf16 v[82:97], v[234:237], v[230:233], v[82:97]
	ds_read_b128 v[234:237], v204 offset:45312
	s_waitcnt lgkmcnt(3)
	v_mfma_f32_32x32x16_bf16 v[66:81], v[194:197], v[230:233], v[66:81]
	s_waitcnt lgkmcnt(1)
	v_mfma_f32_32x32x16_bf16 v[82:97], v[226:229], v[238:241], v[82:97]
	s_waitcnt lgkmcnt(0)
	v_mfma_f32_32x32x16_bf16 v[66:81], v[234:237], v[238:241], v[66:81]
	s_nop 1
	s_cbranch_scc1 .LBB0_736
	s_branch .Lattn_b135
.Lattn_qk2_pf:
	ds_read_b128 v[194:197], v139 offset:57344
	ds_read_b128 v[226:229], v205 offset:12288
	ds_read_b128 v[234:237], v202 offset:57344
	ds_read_b128 v[230:233], v220
	ds_read_b128 v[238:241], v220 offset:1024
	s_add_i32 s0, s84, 0x7f
	s_cmp_le_i32 s0, s82
	s_waitcnt lgkmcnt(4)
	v_mfma_f32_32x32x16_bf16 v[82:97], v[194:197], v[98:101], 0
	ds_read_b128 v[194:197], v206 offset:12288
	s_waitcnt lgkmcnt(4)
	v_mfma_f32_32x32x16_bf16 v[66:81], v[226:229], v[98:101], 0
	global_load_dwordx4 v[114:117], v[242:243], off
	ds_read_b128 v[226:229], v203 offset:57344
	s_waitcnt lgkmcnt(4)
	v_mfma_f32_32x32x16_bf16 v[82:97], v[234:237], v[102:105], v[82:97]
	ds_read_b128 v[234:237], v207 offset:12288
	s_waitcnt lgkmcnt(2)
	v_mfma_f32_32x32x16_bf16 v[66:81], v[194:197], v[102:105], v[66:81]
	global_load_dwordx4 v[118:121], v[244:245], off
	ds_read_b128 v[194:197], v204 offset:57344
	s_waitcnt lgkmcnt(2)
	v_mfma_f32_32x32x16_bf16 v[82:97], v[226:229], v[106:109], v[82:97]
	ds_read_b128 v[226:229], v208 offset:12288
	s_waitcnt lgkmcnt(2)
	v_mfma_f32_32x32x16_bf16 v[66:81], v[234:237], v[106:109], v[66:81]
	global_load_dwordx4 v[122:125], v[246:247], off
	ds_read_b128 v[234:237], v139 offset:57472
	s_waitcnt lgkmcnt(2)
	v_mfma_f32_32x32x16_bf16 v[82:97], v[194:197], v[110:113], v[82:97]
	ds_read_b128 v[194:197], v205 offset:12416
	s_waitcnt lgkmcnt(2)
	v_mfma_f32_32x32x16_bf16 v[66:81], v[226:229], v[110:113], v[66:81]
	global_load_dwordx4 v[126:129], v[248:249], off
	ds_read_b128 v[226:229], v202 offset:57472
	s_waitcnt lgkmcnt(2)
	v_mfma_f32_32x32x16_bf16 v[82:97], v[234:237], v[230:233], v[82:97]
	ds_read_b128 v[234:237], v206 offset:12416
	s_waitcnt lgkmcnt(2)
	v_mfma_f32_32x32x16_bf16 v[66:81], v[194:197], v[230:233], v[66:81]
	global_load_dwordx4 v[130:133], v[250:251], off
	ds_read_b128 v[194:197], v203 offset:57472
	ds_read_b128 v[230:233], v220 offset:2048
	s_waitcnt lgkmcnt(3)
	v_mfma_f32_32x32x16_bf16 v[82:97], v[226:229], v[238:241], v[82:97]
	ds_read_b128 v[226:229], v207 offset:12416
	s_waitcnt lgkmcnt(3)
	v_mfma_f32_32x32x16_bf16 v[66:81], v[234:237], v[238:241], v[66:81]
	ds_read_b128 v[234:237], v204 offset:57472
	ds_read_b128 v[238:241], v220 offset:3072
	s_waitcnt lgkmcnt(3)
	v_mfma_f32_32x32x16_bf16 v[82:97], v[194:197], v[230:233], v[82:97]
	ds_read_b128 v[194:197], v208 offset:12416
	s_waitcnt lgkmcnt(3)
	v_mfma_f32_32x32x16_bf16 v[66:81], v[226:229], v[230:233], v[66:81]
	ds_read_b128 v[226:229], v139 offset:57600
	ds_read_b128 v[230:233], v220 offset:4096
	s_waitcnt lgkmcnt(3)
	v_mfma_f32_32x32x16_bf16 v[82:97], v[234:237], v[238:241], v[82:97]
	ds_read_b128 v[234:237], v205 offset:12544
	s_waitcnt lgkmcnt(3)
	v_mfma_f32_32x32x16_bf16 v[66:81], v[194:197], v[238:241], v[66:81]
	ds_read_b128 v[194:197], v202 offset:57600
	ds_read_b128 v[238:241], v220 offset:5120
	s_waitcnt lgkmcnt(3)
	v_mfma_f32_32x32x16_bf16 v[82:97], v[226:229], v[230:233], v[82:97]
	ds_read_b128 v[226:229], v206 offset:12544
	s_waitcnt lgkmcnt(3)
	v_mfma_f32_32x32x16_bf16 v[66:81], v[234:237], v[230:233], v[66:81]
	ds_read_b128 v[234:237], v203 offset:57600
	ds_read_b128 v[230:233], v220 offset:6144
	s_waitcnt lgkmcnt(3)
	v_mfma_f32_32x32x16_bf16 v[82:97], v[194:197], v[238:241], v[82:97]
	ds_read_b128 v[194:197], v207 offset:12544
	s_waitcnt lgkmcnt(3)
	v_mfma_f32_32x32x16_bf16 v[66:81], v[226:229], v[238:241], v[66:81]
	ds_read_b128 v[226:229], v204 offset:57600
	ds_read_b128 v[238:241], v220 offset:7168
	s_waitcnt lgkmcnt(3)
	v_mfma_f32_32x32x16_bf16 v[82:97], v[234:237], v[230:233], v[82:97]
	ds_read_b128 v[234:237], v208 offset:12544
	s_waitcnt lgkmcnt(3)
	v_mfma_f32_32x32x16_bf16 v[66:81], v[194:197], v[230:233], v[66:81]
	s_waitcnt lgkmcnt(1)
	v_mfma_f32_32x32x16_bf16 v[82:97], v[226:229], v[238:241], v[82:97]
	s_waitcnt lgkmcnt(0)
	v_mfma_f32_32x32x16_bf16 v[66:81], v[234:237], v[238:241], v[66:81]
	s_nop 1
	s_cbranch_scc1 .LBB0_746
	s_branch .Lattn_b235

.LBB0_945:
	s_mov_b32 s32, 0
	s_cmp_lt_i32 s38, 3
	s_mov_b64 s[4:5], -1
	s_cbranch_scc1 .LBB0_954
	s_cmp_lt_i32 s38, 4
	s_cbranch_scc1 .LBB0_951
	s_cmp_lg_u32 s38, 4
	s_mov_b64 s[0:1], -1
	s_cbranch_scc0 .LBB0_949
	s_mov_b64 s[0:1], 0

.LBB0_969:
	s_mov_b32 s32, 1
	s_andn2_b64 vcc, exec, s[6:7]
	s_mov_b32 s44, s64
	s_mov_b32 s3, s65
	s_mov_b64 s[10:11], s[30:31]
	s_mov_b64 s[8:9], s[0:1]
	s_cbranch_vccz .LBB0_1081

.LBB0_976:
	s_add_u32 s8, s8, 0x80
	s_addc_u32 s9, s9, 0
	s_add_u32 s34, s10, 0x100
	v_mov_b32_e32 v2, 0
	s_addc_u32 s35, s11, 0
	s_mov_b32 s10, 0
	s_cmp_eq_u32 s32, 1
	s_cbranch_scc1 .Lg2_first
	v_mov_b32_e32 v3, v2
	v_mov_b32_e32 v4, v2
	v_mov_b32_e32 v5, v2
	v_mov_b32_e32 v6, v2
	v_mov_b32_e32 v7, v2
	v_mov_b32_e32 v8, v2
	v_mov_b32_e32 v9, v2
	v_mov_b32_e32 v18, v2
	v_mov_b32_e32 v19, v2
	v_mov_b32_e32 v20, v2
	v_mov_b32_e32 v21, v2
	v_mov_b32_e32 v22, v2
	v_mov_b32_e32 v23, v2
	v_mov_b32_e32 v24, v2
	v_mov_b32_e32 v25, v2
	v_mov_b32_e32 v34, v2
	v_mov_b32_e32 v35, v2
	v_mov_b32_e32 v36, v2
	v_mov_b32_e32 v37, v2
	v_mov_b32_e32 v38, v2
	v_mov_b32_e32 v39, v2
	v_mov_b32_e32 v40, v2
	v_mov_b32_e32 v41, v2
	v_mov_b32_e32 v50, v2
	v_mov_b32_e32 v51, v2
	v_mov_b32_e32 v52, v2
	v_mov_b32_e32 v53, v2
	v_mov_b32_e32 v54, v2
	v_mov_b32_e32 v55, v2
	v_mov_b32_e32 v56, v2
	v_mov_b32_e32 v57, v2
	v_mov_b32_e32 v10, v2
	v_mov_b32_e32 v11, v2
	v_mov_b32_e32 v12, v2
	v_mov_b32_e32 v13, v2
	v_mov_b32_e32 v14, v2
	v_mov_b32_e32 v15, v2
	v_mov_b32_e32 v16, v2
	v_mov_b32_e32 v17, v2
	v_mov_b32_e32 v26, v2
	v_mov_b32_e32 v27, v2
	v_mov_b32_e32 v28, v2
	v_mov_b32_e32 v29, v2
	v_mov_b32_e32 v30, v2
	v_mov_b32_e32 v31, v2
	v_mov_b32_e32 v32, v2
	v_mov_b32_e32 v33, v2
	v_mov_b32_e32 v42, v2
	v_mov_b32_e32 v43, v2
	v_mov_b32_e32 v44, v2
	v_mov_b32_e32 v45, v2
	v_mov_b32_e32 v46, v2
	v_mov_b32_e32 v47, v2
	v_mov_b32_e32 v48, v2
	v_mov_b32_e32 v49, v2
	v_mov_b32_e32 v58, v2
	v_mov_b32_e32 v59, v2
	v_mov_b32_e32 v60, v2
	v_mov_b32_e32 v61, v2
	v_mov_b32_e32 v62, v2
	v_mov_b32_e32 v63, v2
	v_mov_b32_e32 v64, v2
	v_mov_b32_e32 v65, v2
	v_mov_b32_e32 v66, v2
	v_mov_b32_e32 v67, v2
	v_mov_b32_e32 v68, v2
	v_mov_b32_e32 v69, v2
	v_mov_b32_e32 v70, v2
	v_mov_b32_e32 v71, v2
	v_mov_b32_e32 v72, v2
	v_mov_b32_e32 v73, v2
	v_mov_b32_e32 v82, v2
	v_mov_b32_e32 v83, v2
	v_mov_b32_e32 v84, v2
	v_mov_b32_e32 v85, v2
	v_mov_b32_e32 v86, v2
	v_mov_b32_e32 v87, v2
	v_mov_b32_e32 v88, v2
	v_mov_b32_e32 v89, v2
	v_mov_b32_e32 v98, v2
	v_mov_b32_e32 v99, v2
	v_mov_b32_e32 v100, v2
	v_mov_b32_e32 v101, v2
	v_mov_b32_e32 v102, v2
	v_mov_b32_e32 v103, v2
	v_mov_b32_e32 v104, v2
	v_mov_b32_e32 v105, v2
	v_mov_b32_e32 v114, v2
	v_mov_b32_e32 v115, v2
	v_mov_b32_e32 v116, v2
	v_mov_b32_e32 v117, v2
	v_mov_b32_e32 v118, v2
	v_mov_b32_e32 v119, v2
	v_mov_b32_e32 v120, v2
	v_mov_b32_e32 v121, v2
	v_mov_b32_e32 v74, v2
	v_mov_b32_e32 v75, v2
	v_mov_b32_e32 v76, v2
	v_mov_b32_e32 v77, v2
	v_mov_b32_e32 v78, v2
	v_mov_b32_e32 v79, v2
	v_mov_b32_e32 v80, v2
	v_mov_b32_e32 v81, v2
	v_mov_b32_e32 v90, v2
	v_mov_b32_e32 v91, v2
	v_mov_b32_e32 v92, v2
	v_mov_b32_e32 v93, v2
	v_mov_b32_e32 v94, v2
	v_mov_b32_e32 v95, v2
	v_mov_b32_e32 v96, v2
	v_mov_b32_e32 v97, v2
	v_mov_b32_e32 v106, v2
	v_mov_b32_e32 v107, v2
	v_mov_b32_e32 v108, v2
	v_mov_b32_e32 v109, v2
	v_mov_b32_e32 v110, v2
	v_mov_b32_e32 v111, v2
	v_mov_b32_e32 v112, v2
	v_mov_b32_e32 v113, v2
	v_mov_b32_e32 v122, v2
	v_mov_b32_e32 v123, v2
	v_mov_b32_e32 v124, v2
	v_mov_b32_e32 v125, v2
	v_mov_b32_e32 v126, v2
	v_mov_b32_e32 v127, v2
	v_mov_b32_e32 v128, v2
	v_mov_b32_e32 v129, v2

.Lg2_after:
	s_and_b64 vcc, exec, s[26:27]
	s_cbranch_vccnz .LBB0_981
	s_lshl_b32 s10, s3, 8
	s_cmp_lt_i32 s38, 2
	s_mov_b64 s[8:9], -1
	s_cbranch_scc0 .LBB0_982

.Lg2_first:
	s_mov_b32 s32, 0
	s_add_i32 s36, s10, 2
	s_add_u32 s37, s8, 0x80
	s_addc_u32 s11, s9, 0
	s_add_i32 s66, 0, 0x10000
	s_cmp_eq_u32 s55, s10
	s_cselect_b32 s11, s1, s11
	s_cselect_b32 s10, s0, s37
	v_add_u32_e32 v0, s66, v156
	s_cselect_b32 s59, s31, s35
	s_cselect_b32 s58, s30, s34
	s_add_i32 s37, 0, 0x14000
	ds_read_b128 v[144:147], v0
	ds_read_b128 v[148:151], v0 offset:1024
	ds_read_b128 v[160:163], v0 offset:2048
	ds_read_b128 v[164:167], v0 offset:3072
	v_add_u32_e32 v0, s37, v156
	ds_read_b128 v[168:171], v0
	ds_read_b128 v[172:175], v0 offset:1024
	ds_read_b128 v[176:179], v0 offset:2048
	ds_read_b128 v[180:183], v0 offset:3072
	v_lshl_add_u64 v[218:219], s[8:9], 0, v[140:141]
	s_add_i32 m0, s48, 0xc000
	ds_read_b128 v[184:187], v158
	ds_read_b128 v[188:191], v158 offset:1024
	ds_read_b128 v[192:195], v158 offset:2048
	ds_read_b128 v[196:199], v158 offset:3072
	ds_read_b128 v[202:205], v158 offset:4096
	ds_read_b128 v[206:209], v158 offset:5120
	ds_read_b128 v[210:213], v158 offset:6144
	ds_read_b128 v[214:217], v158 offset:7168
	global_load_lds_dwordx4 v[218:219], off
	v_lshl_add_u64 v[218:219], s[8:9], 0, v[142:143]
	s_add_i32 m0, s48, 0xe000
	s_nop 0
	global_load_lds_dwordx4 v[218:219], off
	s_waitcnt lgkmcnt(0)
	s_barrier
	s_setprio 1
	s_waitcnt lgkmcnt(0)
	v_mfma_f32_16x16x32_bf16 v[126:129], v[144:147], v[184:187], 0
	v_mfma_f32_16x16x32_bf16 v[122:125], v[160:163], v[184:187], 0
	v_mfma_f32_16x16x32_bf16 v[110:113], v[144:147], v[192:195], 0
	v_mfma_f32_16x16x32_bf16 v[106:109], v[160:163], v[192:195], 0
	v_mfma_f32_16x16x32_bf16 v[94:97], v[144:147], v[202:205], 0
	v_mfma_f32_16x16x32_bf16 v[90:93], v[160:163], v[202:205], 0
	v_mfma_f32_16x16x32_bf16 v[78:81], v[144:147], v[210:213], 0
	v_mfma_f32_16x16x32_bf16 v[74:77], v[160:163], v[210:213], 0
	v_mfma_f32_16x16x32_bf16 v[126:129], v[148:151], v[188:191], v[126:129]
	v_mfma_f32_16x16x32_bf16 v[122:125], v[164:167], v[188:191], v[122:125]
	v_mfma_f32_16x16x32_bf16 v[110:113], v[148:151], v[196:199], v[110:113]
	v_mfma_f32_16x16x32_bf16 v[106:109], v[164:167], v[196:199], v[106:109]
	v_mfma_f32_16x16x32_bf16 v[94:97], v[148:151], v[206:209], v[94:97]
	v_mfma_f32_16x16x32_bf16 v[90:93], v[164:167], v[206:209], v[90:93]
	v_mfma_f32_16x16x32_bf16 v[78:81], v[148:151], v[214:217], v[78:81]
	v_mfma_f32_16x16x32_bf16 v[74:77], v[164:167], v[214:217], v[74:77]
	s_setprio 0
	s_setprio 1
	v_mfma_f32_16x16x32_bf16 v[118:121], v[168:171], v[184:187], 0
	v_mfma_f32_16x16x32_bf16 v[114:117], v[176:179], v[184:187], 0
	v_mfma_f32_16x16x32_bf16 v[102:105], v[168:171], v[192:195], 0
	v_mfma_f32_16x16x32_bf16 v[98:101], v[176:179], v[192:195], 0
	v_mfma_f32_16x16x32_bf16 v[86:89], v[168:171], v[202:205], 0
	v_mfma_f32_16x16x32_bf16 v[82:85], v[176:179], v[202:205], 0
	v_mfma_f32_16x16x32_bf16 v[70:73], v[168:171], v[210:213], 0
	v_mfma_f32_16x16x32_bf16 v[66:69], v[176:179], v[210:213], 0
	v_mfma_f32_16x16x32_bf16 v[118:121], v[172:175], v[188:191], v[118:121]
	v_mfma_f32_16x16x32_bf16 v[114:117], v[180:183], v[188:191], v[114:117]
	v_mfma_f32_16x16x32_bf16 v[102:105], v[172:175], v[196:199], v[102:105]
	v_mfma_f32_16x16x32_bf16 v[98:101], v[180:183], v[196:199], v[98:101]
	v_mfma_f32_16x16x32_bf16 v[86:89], v[172:175], v[206:209], v[86:89]
	v_mfma_f32_16x16x32_bf16 v[82:85], v[180:183], v[206:209], v[82:85]
	v_mfma_f32_16x16x32_bf16 v[70:73], v[172:175], v[214:217], v[70:73]
	v_mfma_f32_16x16x32_bf16 v[66:69], v[180:183], v[214:217], v[66:69]
	s_setprio 0
	s_barrier
	s_add_i32 s66, s66, s47
	v_lshl_add_u64 v[218:219], s[58:59], 0, v[136:137]
	s_mov_b32 m0, s66
	ds_read_b128 v[184:187], v158 offset:16384
	ds_read_b128 v[188:191], v158 offset:17408
	ds_read_b128 v[192:195], v158 offset:18432
	ds_read_b128 v[196:199], v158 offset:19456
	ds_read_b128 v[202:205], v158 offset:20480
	ds_read_b128 v[206:209], v158 offset:21504
	ds_read_b128 v[210:213], v158 offset:22528
	ds_read_b128 v[214:217], v158 offset:23552
	global_load_lds_dwordx4 v[218:219], off
	s_add_i32 m0, s66, 0x2000
	v_lshl_add_u64 v[220:221], s[58:59], 0, v[132:133]
	s_add_u32 s58, s58, s45
	s_addc_u32 s59, s59, 0
	s_add_i32 s37, s37, s47
	global_load_lds_dwordx4 v[220:221], off
	v_lshl_add_u64 v[222:223], s[58:59], 0, v[136:137]
	s_mov_b32 m0, s37
	v_lshl_add_u64 v[224:225], s[58:59], 0, v[132:133]
	global_load_lds_dwordx4 v[222:223], off
	s_add_i32 m0, s37, 0x2000
	v_lshl_add_u64 v[226:227], s[10:11], 0, v[134:135]
	global_load_lds_dwordx4 v[224:225], off
	s_mov_b32 m0, s48
	v_lshl_add_u64 v[228:229], s[10:11], 0, v[130:131]
	global_load_lds_dwordx4 v[226:227], off
	s_mov_b32 m0, s49
	s_nop 0
	global_load_lds_dwordx4 v[228:229], off
	s_waitcnt lgkmcnt(0)
	s_barrier
	s_setprio 1
	s_waitcnt lgkmcnt(0)
	v_mfma_f32_16x16x32_bf16 v[62:65], v[144:147], v[184:187], 0
	v_mfma_f32_16x16x32_bf16 v[58:61], v[160:163], v[184:187], 0
	v_mfma_f32_16x16x32_bf16 v[46:49], v[144:147], v[192:195], 0
	v_mfma_f32_16x16x32_bf16 v[42:45], v[160:163], v[192:195], 0
	v_mfma_f32_16x16x32_bf16 v[30:33], v[144:147], v[202:205], 0
	v_mfma_f32_16x16x32_bf16 v[26:29], v[160:163], v[202:205], 0
	v_mfma_f32_16x16x32_bf16 v[14:17], v[144:147], v[210:213], 0
	v_mfma_f32_16x16x32_bf16 v[10:13], v[160:163], v[210:213], 0
	v_mfma_f32_16x16x32_bf16 v[62:65], v[148:151], v[188:191], v[62:65]
	v_mfma_f32_16x16x32_bf16 v[58:61], v[164:167], v[188:191], v[58:61]
	v_mfma_f32_16x16x32_bf16 v[46:49], v[148:151], v[196:199], v[46:49]
	v_mfma_f32_16x16x32_bf16 v[42:45], v[164:167], v[196:199], v[42:45]
	v_mfma_f32_16x16x32_bf16 v[30:33], v[148:151], v[206:209], v[30:33]
	v_mfma_f32_16x16x32_bf16 v[26:29], v[164:167], v[206:209], v[26:29]
	v_mfma_f32_16x16x32_bf16 v[14:17], v[148:151], v[214:217], v[14:17]
	v_mfma_f32_16x16x32_bf16 v[10:13], v[164:167], v[214:217], v[10:13]
	s_setprio 0
	s_setprio 1
	v_mfma_f32_16x16x32_bf16 v[54:57], v[168:171], v[184:187], 0
	v_mfma_f32_16x16x32_bf16 v[50:53], v[176:179], v[184:187], 0
	v_mfma_f32_16x16x32_bf16 v[38:41], v[168:171], v[192:195], 0
	v_mfma_f32_16x16x32_bf16 v[34:37], v[176:179], v[192:195], 0
	v_mfma_f32_16x16x32_bf16 v[22:25], v[168:171], v[202:205], 0
	v_mfma_f32_16x16x32_bf16 v[18:21], v[176:179], v[202:205], 0
	v_mfma_f32_16x16x32_bf16 v[6:9], v[168:171], v[210:213], 0
	v_mfma_f32_16x16x32_bf16 v[2:5], v[176:179], v[210:213], 0
	v_mfma_f32_16x16x32_bf16 v[54:57], v[172:175], v[188:191], v[54:57]
	v_mfma_f32_16x16x32_bf16 v[50:53], v[180:183], v[188:191], v[50:53]
	v_mfma_f32_16x16x32_bf16 v[38:41], v[172:175], v[196:199], v[38:41]
	v_mfma_f32_16x16x32_bf16 v[34:37], v[180:183], v[196:199], v[34:37]
	v_mfma_f32_16x16x32_bf16 v[22:25], v[172:175], v[206:209], v[22:25]
	v_mfma_f32_16x16x32_bf16 v[18:21], v[180:183], v[206:209], v[18:21]
	v_mfma_f32_16x16x32_bf16 v[6:9], v[172:175], v[214:217], v[6:9]
	v_mfma_f32_16x16x32_bf16 v[2:5], v[180:183], v[214:217], v[2:5]
	s_setprio 0
	s_barrier
	s_add_i32 s37, 0, 0x18000
	v_add_u32_e32 v0, s37, v156
	s_add_i32 s58, 0, 0x1c000
	ds_read_b128 v[144:147], v0
	ds_read_b128 v[148:151], v0 offset:1024
	ds_read_b128 v[160:163], v0 offset:2048
	ds_read_b128 v[164:167], v0 offset:3072
	v_add_u32_e32 v0, s58, v156
	ds_read_b128 v[168:171], v0
	ds_read_b128 v[172:175], v0 offset:1024
	ds_read_b128 v[176:179], v0 offset:2048
	ds_read_b128 v[180:183], v0 offset:3072
	s_add_u32 s10, s10, s12
	s_addc_u32 s11, s11, 0
	s_mov_b32 m0, s50
	v_lshl_add_u64 v[230:231], s[10:11], 0, v[134:135]
	ds_read_b128 v[184:187], v158 offset:32768
	ds_read_b128 v[188:191], v158 offset:33792
	ds_read_b128 v[192:195], v158 offset:34816
	ds_read_b128 v[196:199], v158 offset:35840
	ds_read_b128 v[202:205], v158 offset:36864
	ds_read_b128 v[206:209], v158 offset:37888
	ds_read_b128 v[210:213], v158 offset:38912
	ds_read_b128 v[214:217], v158 offset:39936
	global_load_lds_dwordx4 v[230:231], off
	v_lshl_add_u64 v[230:231], s[10:11], 0, v[130:131]
	s_mov_b32 m0, s51
	s_nop 0
	global_load_lds_dwordx4 v[230:231], off
	s_waitcnt vmcnt(8)
	s_waitcnt lgkmcnt(0)
	s_barrier
	s_setprio 1
	s_waitcnt lgkmcnt(0)
	v_mfma_f32_16x16x32_bf16 v[126:129], v[144:147], v[184:187], v[126:129]
	v_mfma_f32_16x16x32_bf16 v[122:125], v[160:163], v[184:187], v[122:125]
	v_mfma_f32_16x16x32_bf16 v[110:113], v[144:147], v[192:195], v[110:113]
	v_mfma_f32_16x16x32_bf16 v[106:109], v[160:163], v[192:195], v[106:109]
	v_mfma_f32_16x16x32_bf16 v[94:97], v[144:147], v[202:205], v[94:97]
	v_mfma_f32_16x16x32_bf16 v[90:93], v[160:163], v[202:205], v[90:93]
	v_mfma_f32_16x16x32_bf16 v[78:81], v[144:147], v[210:213], v[78:81]
	v_mfma_f32_16x16x32_bf16 v[74:77], v[160:163], v[210:213], v[74:77]
	v_mfma_f32_16x16x32_bf16 v[126:129], v[148:151], v[188:191], v[126:129]
	v_mfma_f32_16x16x32_bf16 v[122:125], v[164:167], v[188:191], v[122:125]
	v_mfma_f32_16x16x32_bf16 v[110:113], v[148:151], v[196:199], v[110:113]
	v_mfma_f32_16x16x32_bf16 v[106:109], v[164:167], v[196:199], v[106:109]
	v_mfma_f32_16x16x32_bf16 v[94:97], v[148:151], v[206:209], v[94:97]
	v_mfma_f32_16x16x32_bf16 v[90:93], v[164:167], v[206:209], v[90:93]
	v_mfma_f32_16x16x32_bf16 v[78:81], v[148:151], v[214:217], v[78:81]
	v_mfma_f32_16x16x32_bf16 v[74:77], v[164:167], v[214:217], v[74:77]
	s_setprio 0
	s_setprio 1
	v_mfma_f32_16x16x32_bf16 v[118:121], v[168:171], v[184:187], v[118:121]
	v_mfma_f32_16x16x32_bf16 v[114:117], v[176:179], v[184:187], v[114:117]
	v_mfma_f32_16x16x32_bf16 v[102:105], v[168:171], v[192:195], v[102:105]
	v_mfma_f32_16x16x32_bf16 v[98:101], v[176:179], v[192:195], v[98:101]
	v_mfma_f32_16x16x32_bf16 v[86:89], v[168:171], v[202:205], v[86:89]
	v_mfma_f32_16x16x32_bf16 v[82:85], v[176:179], v[202:205], v[82:85]
	v_mfma_f32_16x16x32_bf16 v[70:73], v[168:171], v[210:213], v[70:73]
	v_mfma_f32_16x16x32_bf16 v[66:69], v[176:179], v[210:213], v[66:69]
	v_mfma_f32_16x16x32_bf16 v[118:121], v[172:175], v[188:191], v[118:121]
	v_mfma_f32_16x16x32_bf16 v[114:117], v[180:183], v[188:191], v[114:117]
	v_mfma_f32_16x16x32_bf16 v[102:105], v[172:175], v[196:199], v[102:105]
	v_mfma_f32_16x16x32_bf16 v[98:101], v[180:183], v[196:199], v[98:101]
	v_mfma_f32_16x16x32_bf16 v[86:89], v[172:175], v[206:209], v[86:89]
	v_mfma_f32_16x16x32_bf16 v[82:85], v[180:183], v[206:209], v[82:85]
	v_mfma_f32_16x16x32_bf16 v[70:73], v[172:175], v[214:217], v[70:73]
	v_mfma_f32_16x16x32_bf16 v[66:69], v[180:183], v[214:217], v[66:69]
	s_setprio 0
	s_barrier
	s_add_i32 s10, s37, s47
	v_lshl_add_u64 v[218:219], v[218:219], 0, s[14:15]
	s_mov_b32 m0, s10
	ds_read_b128 v[184:187], v158 offset:49152
	ds_read_b128 v[188:191], v158 offset:50176
	ds_read_b128 v[192:195], v158 offset:51200
	ds_read_b128 v[196:199], v158 offset:52224
	ds_read_b128 v[202:205], v158 offset:53248
	ds_read_b128 v[206:209], v158 offset:54272
	ds_read_b128 v[210:213], v158 offset:55296
	ds_read_b128 v[214:217], v158 offset:56320
	global_load_lds_dwordx4 v[218:219], off
	v_lshl_add_u64 v[218:219], v[220:221], 0, s[14:15]
	s_add_i32 m0, s10, 0x2000
	s_add_i32 s10, s58, s47
	global_load_lds_dwordx4 v[218:219], off
	v_lshl_add_u64 v[218:219], v[222:223], 0, s[14:15]
	s_mov_b32 m0, s10
	s_nop 0
	global_load_lds_dwordx4 v[218:219], off
	v_lshl_add_u64 v[218:219], v[224:225], 0, s[14:15]
	s_add_i32 m0, s10, 0x2000
	s_nop 0
	global_load_lds_dwordx4 v[218:219], off
	v_lshl_add_u64 v[218:219], v[226:227], 0, s[14:15]
	s_mov_b32 m0, s53
	s_nop 0
	global_load_lds_dwordx4 v[218:219], off
	v_lshl_add_u64 v[218:219], v[228:229], 0, s[14:15]
	s_mov_b32 m0, s54
	s_nop 0
	global_load_lds_dwordx4 v[218:219], off
	s_waitcnt vmcnt(8)
	s_waitcnt lgkmcnt(0)
	s_barrier
	s_setprio 1
	s_waitcnt lgkmcnt(0)
	v_mfma_f32_16x16x32_bf16 v[62:65], v[144:147], v[184:187], v[62:65]
	v_mfma_f32_16x16x32_bf16 v[58:61], v[160:163], v[184:187], v[58:61]
	v_mfma_f32_16x16x32_bf16 v[46:49], v[144:147], v[192:195], v[46:49]
	v_mfma_f32_16x16x32_bf16 v[42:45], v[160:163], v[192:195], v[42:45]
	v_mfma_f32_16x16x32_bf16 v[30:33], v[144:147], v[202:205], v[30:33]
	v_mfma_f32_16x16x32_bf16 v[26:29], v[160:163], v[202:205], v[26:29]
	v_mfma_f32_16x16x32_bf16 v[14:17], v[144:147], v[210:213], v[14:17]
	v_mfma_f32_16x16x32_bf16 v[10:13], v[160:163], v[210:213], v[10:13]
	v_mfma_f32_16x16x32_bf16 v[62:65], v[148:151], v[188:191], v[62:65]
	v_mfma_f32_16x16x32_bf16 v[58:61], v[164:167], v[188:191], v[58:61]
	v_mfma_f32_16x16x32_bf16 v[46:49], v[148:151], v[196:199], v[46:49]
	v_mfma_f32_16x16x32_bf16 v[42:45], v[164:167], v[196:199], v[42:45]
	v_mfma_f32_16x16x32_bf16 v[30:33], v[148:151], v[206:209], v[30:33]
	v_mfma_f32_16x16x32_bf16 v[26:29], v[164:167], v[206:209], v[26:29]
	v_mfma_f32_16x16x32_bf16 v[14:17], v[148:151], v[214:217], v[14:17]
	v_mfma_f32_16x16x32_bf16 v[10:13], v[164:167], v[214:217], v[10:13]
	s_setprio 0
	s_setprio 1
	v_mfma_f32_16x16x32_bf16 v[54:57], v[168:171], v[184:187], v[54:57]
	v_mfma_f32_16x16x32_bf16 v[50:53], v[176:179], v[184:187], v[50:53]
	v_mfma_f32_16x16x32_bf16 v[38:41], v[168:171], v[192:195], v[38:41]
	v_mfma_f32_16x16x32_bf16 v[34:37], v[176:179], v[192:195], v[34:37]
	v_mfma_f32_16x16x32_bf16 v[22:25], v[168:171], v[202:205], v[22:25]
	v_mfma_f32_16x16x32_bf16 v[18:21], v[176:179], v[202:205], v[18:21]
	v_mfma_f32_16x16x32_bf16 v[6:9], v[168:171], v[210:213], v[6:9]
	v_mfma_f32_16x16x32_bf16 v[2:5], v[176:179], v[210:213], v[2:5]
	v_mfma_f32_16x16x32_bf16 v[54:57], v[172:175], v[188:191], v[54:57]
	v_mfma_f32_16x16x32_bf16 v[50:53], v[180:183], v[188:191], v[50:53]
	v_mfma_f32_16x16x32_bf16 v[38:41], v[172:175], v[196:199], v[38:41]
	v_mfma_f32_16x16x32_bf16 v[34:37], v[180:183], v[196:199], v[34:37]
	v_mfma_f32_16x16x32_bf16 v[22:25], v[172:175], v[206:209], v[22:25]
	v_mfma_f32_16x16x32_bf16 v[18:21], v[180:183], v[206:209], v[18:21]
	v_mfma_f32_16x16x32_bf16 v[6:9], v[172:175], v[214:217], v[6:9]
	v_mfma_f32_16x16x32_bf16 v[2:5], v[180:183], v[214:217], v[2:5]
	s_setprio 0
	s_barrier
	s_add_u32 s8, s8, 0x100
	s_addc_u32 s9, s9, 0
	s_add_u32 s34, s34, 0x100
	s_addc_u32 s35, s35, 0
	s_cmp_ge_u32 s36, s52
	s_mov_b32 s10, s36
	s_cbranch_scc0 .LBB0_977
	s_branch .Lg2_after
